# norm loops as before plus the one-state pad after two packed ops whose spacing instruction had been removed
# speedup vs baseline: 1.0096x; 1.0096x over previous
; #define GAS __attribute__((address_space(1)))
; DI void phase_norm(const Ctx& C, const float* xlat, const float* xctx, bf16_t* H, const float* gn, const float* modl, int sh_off, int sc_off, int nrows, const float* part, int nsplit, float* xs_out) {
;     ...
;     for (int row = gw; row < nrows; row += NGW) {
;         const int b = row < NLAT ? (row >> 11) : 4;
;         const float* mb = modl + (size_t)b * MODW;
;         const GAS f32x4* xr = (const GAS f32x4*)(row < NLAT ? xlat + (size_t)row * DM : xctx + (size_t)(row - NLAT) * DM) + lane;
;         f32x4 v[8]; float s = 0.f;
; #pragma unroll
;         for (int j = 0; j < 8; ++j) v[j] = __builtin_nontemporal_load(xr + 64 * j);
;         if (part != nullptr && row >= NLAT) {
;             for (int kb = 0; kb < nsplit; kb += 4) {
;                 f32x4 t[4][8];
; #pragma unroll
;                 for (int q = 0; q < 4; ++q) { const GAS f32x4* pr = (const GAS f32x4*)(part + ((size_t)(kb + q) * NCTX + (row - NLAT)) * DM) + lane;
; #pragma unroll
;                     for (int j = 0; j < 8; ++j) t[q][j] = __builtin_nontemporal_load(pr + 64 * j); }
; #pragma unroll
;                 for (int j = 0; j < 8; ++j) v[j] += (t[0][j] + t[1][j]) + (t[2][j] + t[3][j]); }
;             GAS f32x4* xo = (GAS f32x4*)(xs_out + (size_t)row * DM) + lane;
; #pragma unroll
;             for (int j = 0; j < 8; ++j) xo[64 * j] = v[j];
;         }
; #pragma unroll
;         for (int j = 0; j < 8; ++j) s += (v[j].x * v[j].x + v[j].y * v[j].y) + (v[j].z * v[j].z + v[j].w * v[j].w);
;         const float rstd = 1.f / sqrtf(wave_sum(s, lane) * (1.f / DM) + EPS);
;         GAS u32x2* o8 = (GAS u32x2*)(H + (size_t)row * DM) + lane;
; #pragma unroll
;         for (int j = 0; j < 8; ++j) { const int col = 4 * lane + 256 * j;
;             const f32x4 g = *(const GAS f32x4*)(gn + col), sc = *(const GAS f32x4*)(mb + sc_off + col), sh = *(const GAS f32x4*)(mb + sh_off + col);
.LBB0_685:
	s_waitcnt vmcnt(0)
	v_mov_b32_e32 v36, v31
	v_mov_b32_e32 v37, v27
	v_mov_b32_e32 v34, v30
	v_mov_b32_e32 v35, v26
	v_pk_mul_f32 v[36:37], v[36:37], v[36:37]
	v_mov_b32_e32 v38, v33
	v_mov_b32_e32 v39, v29
	v_pk_fma_f32 v[34:35], v[34:35], v[34:35], v[36:37]
	v_mov_b32_e32 v36, v32
	v_mov_b32_e32 v37, v28
	v_pk_mul_f32 v[38:39], v[38:39], v[38:39]
	s_min_i32 s0, s4, 0x2000
	v_pk_fma_f32 v[36:37], v[36:37], v[36:37], v[38:39]
	v_pk_mul_f32 v[38:39], v[22:23], v[22:23]
	v_pk_add_f32 v[34:35], v[34:35], v[36:37]
	v_pk_mul_f32 v[36:37], v[24:25], v[24:25]
	v_pk_add_f32 v[34:35], v[34:35], v[34:35] op_sel:[0,1] op_sel_hi:[1,0]
	v_pk_mov_b32 v[40:41], v[38:39], v[36:37] op_sel:[1,0]
	v_mov_b32_e32 v39, v37
	v_pk_add_f32 v[36:37], v[40:41], v[38:39]
	v_mul_f32_e32 v38, v14, v14
	v_mul_f32_e32 v39, v15, v15
	v_pk_add_f32 v[36:37], v[36:37], v[36:37] op_sel:[0,1] op_sel_hi:[1,0]
	v_mov_b32_e32 v35, v38
	v_mov_b32_e32 v37, v39
	v_pk_add_f32 v[34:35], v[34:35], v[36:37]
	v_mul_f32_e32 v36, v19, v19
	v_mul_f32_e32 v38, v21, v21
	v_mul_f32_e32 v40, v16, v16
	v_mul_f32_e32 v41, v17, v17
	v_pk_fma_f32 v[36:37], v[18:19], v[18:19], v[36:37] op_sel_hi:[1,1,0]
	v_pk_fma_f32 v[38:39], v[20:21], v[20:21], v[38:39] op_sel_hi:[1,1,0]
	v_mov_b32_e32 v37, v40
	v_mov_b32_e32 v39, v41
	v_pk_add_f32 v[36:37], v[36:37], v[38:39]
	v_pk_mul_f32 v[38:39], v[10:11], v[10:11]
	v_pk_add_f32 v[34:35], v[34:35], v[36:37]
	v_pk_mul_f32 v[36:37], v[12:13], v[12:13]
	s_ashr_i32 s0, s0, 11
	v_pk_mov_b32 v[40:41], v[38:39], v[36:37] op_sel:[1,0]
	v_mov_b32_e32 v39, v37
	v_pk_add_f32 v[36:37], v[40:41], v[38:39]
	v_mul_f32_e32 v38, v2, v2
	v_mul_f32_e32 v39, v3, v3
	v_pk_add_f32 v[34:35], v[34:35], v[34:35] op_sel:[0,1] op_sel_hi:[1,0]
	v_pk_add_f32 v[36:37], v[36:37], v[36:37] op_sel:[0,1] op_sel_hi:[1,0]
	s_mul_hi_i32 s1, s0, 0xc000
	s_mul_i32 s0, s0, 0xc000
	v_mov_b32_e32 v35, v38
	v_mov_b32_e32 v37, v39
	s_add_u32 s0, s92, s0
	v_pk_add_f32 v[34:35], v[34:35], v[36:37]
	v_mul_f32_e32 v36, v7, v7
	v_mul_f32_e32 v38, v9, v9
	s_addc_u32 s1, s56, s1
	v_mul_f32_e32 v40, v4, v4
	v_mul_f32_e32 v41, v5, v5
	v_pk_fma_f32 v[36:37], v[6:7], v[6:7], v[36:37] op_sel_hi:[1,1,0]
	v_pk_fma_f32 v[38:39], v[8:9], v[8:9], v[38:39] op_sel_hi:[1,1,0]
	v_mov_b32_e32 v37, v40
	v_mov_b32_e32 v39, v41
	v_lshl_add_u64 v[46:47], v[122:123], 2, s[0:1]
	v_pk_add_f32 v[36:37], v[36:37], v[38:39]
	v_add_co_u32_e32 v48, vcc, s20, v46
	v_pk_add_f32 v[34:35], v[34:35], v[36:37]
	s_nop 0
	v_addc_co_u32_e32 v49, vcc, 0, v47, vcc
	v_add_f32_e32 v50, v34, v35
	global_load_dwordx4 v[34:37], v[124:125], off
	global_load_dwordx4 v[38:41], v[48:49], off offset:-4096
	global_load_dwordx4 v[42:45], v[46:47], off
	v_lshl_add_u64 v[134:135], v[46:47], 0, s[44:45]
	v_add_co_u32_e32 v154, vcc, s41, v46
	s_nop 1
	v_addc_co_u32_e32 v155, vcc, 0, v47, vcc
	global_load_dwordx4 v[68:71], v[124:125], off offset:1024
	global_load_dwordx4 v[72:75], v[134:135], off offset:1024
	global_load_dwordx4 v[76:79], v[46:47], off offset:1024
	global_load_dwordx4 v[80:83], v[124:125], off offset:2048
	global_load_dwordx4 v[138:141], v[134:135], off offset:2048
	global_load_dwordx4 v[142:145], v[46:47], off offset:2048
	global_load_dwordx4 v[146:149], v[124:125], off offset:3072
	global_load_dwordx4 v[150:153], v[134:135], off offset:3072
	global_load_dwordx4 v[158:161], v[46:47], off offset:3072
	global_load_dwordx4 v[162:165], v[126:127], off
	global_load_dwordx4 v[174:177], v[48:49], off
	global_load_dwordx4 v[178:181], v[154:155], off
	global_load_dwordx4 v[182:185], v[128:129], off
	global_load_dwordx4 v[186:189], v[48:49], off offset:1024
	global_load_dwordx4 v[190:193], v[154:155], off offset:1024
	global_load_dwordx4 v[202:205], v[130:131], off
	global_load_dwordx4 v[210:213], v[48:49], off offset:2048
	global_load_dwordx4 v[214:217], v[154:155], off offset:2048
	global_load_dwordx4 v[218:221], v[132:133], off
	global_load_dwordx4 v[222:225], v[48:49], off offset:3072
	global_load_dwordx4 v[240:243], v[154:155], off offset:3072
	ds_bpermute_b32 v51, v0, v50
	s_add_u32 s4, s4, s6
	s_addc_u32 s5, s5, s7
	s_waitcnt lgkmcnt(0)
	v_add_f32_e32 v50, v50, v51
	ds_bpermute_b32 v51, v168, v50
	s_waitcnt lgkmcnt(0)
	v_add_f32_e32 v50, v50, v51
	ds_bpermute_b32 v51, v169, v50
	s_waitcnt lgkmcnt(0)
	v_add_f32_e32 v50, v50, v51
	ds_bpermute_b32 v51, v170, v50
	s_waitcnt lgkmcnt(0)
	v_add_f32_e32 v50, v50, v51
	ds_bpermute_b32 v51, v171, v50
	s_waitcnt lgkmcnt(0)
	v_add_f32_e32 v50, v50, v51
	ds_bpermute_b32 v51, v172, v50
	s_waitcnt lgkmcnt(0)
; #define GAS __attribute__((address_space(1)))
; DI unsigned pk2(float lo, float hi) { f32x2 v = {lo, hi}; bf16x2_t b = __builtin_convertvector(v, bf16x2_t); return __builtin_bit_cast(unsigned, b); }
; DI void phase_norm(const Ctx& C, const float* xlat, const float* xctx, bf16_t* H, const float* gn, const float* modl, int sh_off, int sc_off, int nrows, const float* part, int nsplit, float* xs_out) {
;     ...
;         const float rstd = 1.f / sqrtf(wave_sum(s, lane) * (1.f / DM) + EPS);
;         GAS u32x2* o8 = (GAS u32x2*)(H + (size_t)row * DM) + lane;
; #pragma unroll
;         for (int j = 0; j < 8; ++j) { const int col = 4 * lane + 256 * j;
;             const f32x4 g = *(const GAS f32x4*)(gn + col), sc = *(const GAS f32x4*)(mb + sc_off + col), sh = *(const GAS f32x4*)(mb + sh_off + col);
;             const f32x4 y = v[j] * rstd * g * (sc + 1.f) + sh;
;             u32x2 w; w.x = pk2(y.x, y.y); w.y = pk2(y.z, y.w); o8[64 * j] = w; }
	v_add_f32_e32 v50, v50, v51
	v_fmamk_f32 v50, v50, 0x3a000000, v227
	v_mul_f32_e32 v51, 0x4f800000, v50
	v_cmp_gt_f32_e32 vcc, s67, v50
	s_nop 1
	v_cndmask_b32_e32 v50, v50, v51, vcc
	v_sqrt_f32_e32 v51, v50
	s_nop 0
	v_add_u32_e32 v52, -1, v51
	v_fma_f32 v53, -v52, v51, v50
	v_cmp_ge_f32_e64 s[0:1], 0, v53
	v_add_u32_e32 v53, 1, v51
	s_nop 0
	v_cndmask_b32_e64 v52, v51, v52, s[0:1]
	v_fma_f32 v51, -v53, v51, v50
	v_cmp_lt_f32_e64 s[0:1], 0, v51
	s_nop 1
	v_cndmask_b32_e64 v51, v52, v53, s[0:1]
	v_mul_f32_e32 v52, 0x37800000, v51
	v_cndmask_b32_e32 v51, v51, v52, vcc
	v_cmp_class_f32_e32 vcc, v50, v228
	s_nop 1
	v_cndmask_b32_e32 v50, v51, v50, vcc
	v_div_scale_f32 v51, s[0:1], v50, v50, 1.0
	v_rcp_f32_e32 v52, v51
	s_nop 0
	v_fma_f32 v53, -v51, v52, 1.0
	v_fmac_f32_e32 v52, v53, v52
	v_div_scale_f32 v53, vcc, 1.0, v50, 1.0
	v_mul_f32_e32 v54, v53, v52
	v_fma_f32 v55, -v51, v54, v53
	v_fmac_f32_e32 v54, v55, v52
	v_fma_f32 v51, -v51, v54, v53
	v_div_fmas_f32 v51, v51, v52, v54
	v_div_fixup_f32 v50, v51, v50, 1.0
	v_pk_mul_f32 v[32:33], v[32:33], v[50:51] op_sel_hi:[1,0]
	v_pk_mul_f32 v[30:31], v[30:31], v[50:51] op_sel_hi:[1,0]
	s_waitcnt vmcnt(0)
	v_pk_mul_f32 v[32:33], v[36:37], v[32:33]
	v_pk_mul_f32 v[30:31], v[34:35], v[30:31]
	v_pk_add_f32 v[34:35], v[40:41], 1.0 op_sel_hi:[1,0]
	v_pk_add_f32 v[36:37], v[38:39], 1.0 op_sel_hi:[1,0]
	v_pk_fma_f32 v[32:33], v[34:35], v[32:33], v[44:45]
	v_pk_fma_f32 v[30:31], v[36:37], v[30:31], v[42:43]
	v_lshl_add_u64 v[52:53], v[206:207], 3, s[8:9]
	v_cvt_pk_bf16_f32 v30, v30, v31
	v_cvt_pk_bf16_f32 v31, v32, v33
	global_store_dwordx2 v[52:53], v[30:31], off
	v_pk_mul_f32 v[28:29], v[28:29], v[50:51] op_sel_hi:[1,0]
	v_pk_mul_f32 v[26:27], v[26:27], v[50:51] op_sel_hi:[1,0]
	v_pk_mul_f32 v[24:25], v[24:25], v[50:51] op_sel_hi:[1,0]
	v_pk_mul_f32 v[22:23], v[22:23], v[50:51] op_sel_hi:[1,0]
	v_pk_mul_f32 v[20:21], v[20:21], v[50:51] op_sel_hi:[1,0]
	v_pk_mul_f32 v[18:19], v[18:19], v[50:51] op_sel_hi:[1,0]
	v_pk_mul_f32 v[16:17], v[16:17], v[50:51] op_sel_hi:[1,0]
	v_pk_mul_f32 v[14:15], v[14:15], v[50:51] op_sel_hi:[1,0]
	v_pk_mul_f32 v[12:13], v[12:13], v[50:51] op_sel_hi:[1,0]
	v_pk_mul_f32 v[10:11], v[10:11], v[50:51] op_sel_hi:[1,0]
	v_pk_mul_f32 v[8:9], v[8:9], v[50:51] op_sel_hi:[1,0]
	v_pk_mul_f32 v[6:7], v[6:7], v[50:51] op_sel_hi:[1,0]
	v_pk_mul_f32 v[4:5], v[4:5], v[50:51] op_sel_hi:[1,0]
	v_pk_mul_f32 v[2:3], v[2:3], v[50:51] op_sel_hi:[1,0]
	s_add_u32 s8, s8, s10
	s_addc_u32 s9, s9, s11
	s_cmpk_gt_i32 s4, 0x23ff
	v_pk_mul_f32 v[26:27], v[68:69], v[26:27]
	v_pk_mul_f32 v[28:29], v[70:71], v[28:29]
	v_pk_add_f32 v[30:31], v[74:75], 1.0 op_sel_hi:[1,0]
	v_pk_add_f32 v[32:33], v[72:73], 1.0 op_sel_hi:[1,0]
	v_pk_fma_f32 v[28:29], v[30:31], v[28:29], v[78:79]
	v_pk_fma_f32 v[26:27], v[32:33], v[26:27], v[76:77]
	s_nop 0
	v_cvt_pk_bf16_f32 v26, v26, v27
	v_cvt_pk_bf16_f32 v27, v28, v29
	global_store_dwordx2 v[52:53], v[26:27], off offset:512
	s_nop 0
	v_pk_mul_f32 v[22:23], v[80:81], v[22:23]
	v_pk_mul_f32 v[24:25], v[82:83], v[24:25]
	v_pk_add_f32 v[26:27], v[140:141], 1.0 op_sel_hi:[1,0]
	v_pk_add_f32 v[28:29], v[138:139], 1.0 op_sel_hi:[1,0]
	v_pk_fma_f32 v[24:25], v[26:27], v[24:25], v[144:145]
	v_pk_fma_f32 v[22:23], v[28:29], v[22:23], v[142:143]
	s_nop 0
	v_cvt_pk_bf16_f32 v22, v22, v23
	v_cvt_pk_bf16_f32 v23, v24, v25
	global_store_dwordx2 v[52:53], v[22:23], off offset:1024
	s_nop 0
	v_pk_mul_f32 v[18:19], v[18:19], v[146:147]
	v_pk_mul_f32 v[20:21], v[20:21], v[148:149]
	v_pk_add_f32 v[22:23], v[152:153], 1.0 op_sel_hi:[1,0]
	v_pk_add_f32 v[24:25], v[150:151], 1.0 op_sel_hi:[1,0]
	v_pk_fma_f32 v[20:21], v[20:21], v[22:23], v[160:161]
	v_pk_fma_f32 v[18:19], v[18:19], v[24:25], v[158:159]
	s_nop 0
	v_cvt_pk_bf16_f32 v18, v18, v19
	v_cvt_pk_bf16_f32 v19, v20, v21
	global_store_dwordx2 v[52:53], v[18:19], off offset:1536
	s_nop 0
	v_pk_mul_f32 v[14:15], v[14:15], v[162:163]
	v_pk_mul_f32 v[16:17], v[16:17], v[164:165]
	v_pk_add_f32 v[18:19], v[176:177], 1.0 op_sel_hi:[1,0]
	v_pk_add_f32 v[20:21], v[174:175], 1.0 op_sel_hi:[1,0]
	v_pk_fma_f32 v[16:17], v[16:17], v[18:19], v[180:181]
	v_pk_fma_f32 v[14:15], v[14:15], v[20:21], v[178:179]
	s_nop 0
	v_cvt_pk_bf16_f32 v14, v14, v15
	v_cvt_pk_bf16_f32 v15, v16, v17
	global_store_dwordx2 v[52:53], v[14:15], off offset:2048
	s_nop 0
	v_pk_mul_f32 v[10:11], v[10:11], v[182:183]
	v_pk_mul_f32 v[12:13], v[12:13], v[184:185]
	v_pk_add_f32 v[14:15], v[188:189], 1.0 op_sel_hi:[1,0]
	v_pk_add_f32 v[16:17], v[186:187], 1.0 op_sel_hi:[1,0]
	v_pk_fma_f32 v[12:13], v[12:13], v[14:15], v[192:193]
	v_pk_fma_f32 v[10:11], v[10:11], v[16:17], v[190:191]
	s_nop 0
	v_cvt_pk_bf16_f32 v10, v10, v11
	v_cvt_pk_bf16_f32 v11, v12, v13
	global_store_dwordx2 v[52:53], v[10:11], off offset:2560
	s_nop 0
	v_pk_mul_f32 v[6:7], v[6:7], v[202:203]
	v_pk_mul_f32 v[8:9], v[8:9], v[204:205]
	v_pk_add_f32 v[10:11], v[212:213], 1.0 op_sel_hi:[1,0]
	v_pk_add_f32 v[12:13], v[210:211], 1.0 op_sel_hi:[1,0]
	v_pk_fma_f32 v[8:9], v[8:9], v[10:11], v[216:217]
	v_pk_fma_f32 v[6:7], v[6:7], v[12:13], v[214:215]
	s_nop 0
	v_cvt_pk_bf16_f32 v6, v6, v7
	v_cvt_pk_bf16_f32 v7, v8, v9
	global_store_dwordx2 v[52:53], v[6:7], off offset:3072
	s_nop 0
	v_pk_mul_f32 v[2:3], v[2:3], v[218:219]
	v_pk_mul_f32 v[4:5], v[4:5], v[220:221]
	v_pk_add_f32 v[6:7], v[224:225], 1.0 op_sel_hi:[1,0]
	v_pk_add_f32 v[8:9], v[222:223], 1.0 op_sel_hi:[1,0]
	v_pk_fma_f32 v[4:5], v[4:5], v[6:7], v[242:243]
	v_pk_fma_f32 v[2:3], v[2:3], v[8:9], v[240:241]
	s_nop 0
	v_cvt_pk_bf16_f32 v2, v2, v3
	v_cvt_pk_bf16_f32 v3, v4, v5
	global_store_dwordx2 v[52:53], v[2:3], off offset:3584
	s_cbranch_scc1 .LBB0_688

; #define GAS __attribute__((address_space(1)))
; DI void phase_norm(const Ctx& C, const float* xlat, const float* xctx, bf16_t* H, const float* gn, const float* modl, int sh_off, int sc_off, int nrows, const float* part, int nsplit, float* xs_out) {
;     ...
;     for (int row = gw; row < nrows; row += NGW) {
;         const int b = row < NLAT ? (row >> 11) : 4;
;         const float* mb = modl + (size_t)b * MODW;
;         const GAS f32x4* xr = (const GAS f32x4*)(row < NLAT ? xlat + (size_t)row * DM : xctx + (size_t)(row - NLAT) * DM) + lane;
;         f32x4 v[8]; float s = 0.f;
; #pragma unroll
;         for (int j = 0; j < 8; ++j) v[j] = __builtin_nontemporal_load(xr + 64 * j);
;         if (part != nullptr && row >= NLAT) {
;             for (int kb = 0; kb < nsplit; kb += 4) {
;                 f32x4 t[4][8];
; #pragma unroll
;                 for (int q = 0; q < 4; ++q) { const GAS f32x4* pr = (const GAS f32x4*)(part + ((size_t)(kb + q) * NCTX + (row - NLAT)) * DM) + lane;
; #pragma unroll
;                     for (int j = 0; j < 8; ++j) t[q][j] = __builtin_nontemporal_load(pr + 64 * j); }
; #pragma unroll
;                 for (int j = 0; j < 8; ++j) v[j] += (t[0][j] + t[1][j]) + (t[2][j] + t[3][j]); }
;             GAS f32x4* xo = (GAS f32x4*)(xs_out + (size_t)row * DM) + lane;
; #pragma unroll
;             for (int j = 0; j < 8; ++j) xo[64 * j] = v[j];
;         }
; #pragma unroll
;         for (int j = 0; j < 8; ++j) s += (v[j].x * v[j].x + v[j].y * v[j].y) + (v[j].z * v[j].z + v[j].w * v[j].w);
;         const float rstd = 1.f / sqrtf(wave_sum(s, lane) * (1.f / DM) + EPS);
.LBB0_692:
	s_min_i32 s0, s4, 0x2000
	s_ashr_i32 s0, s0, 11
	s_mul_hi_i32 s1, s0, 0xc000
	s_mul_i32 s0, s0, 0xc000
	s_add_u32 s12, s92, s0
	s_addc_u32 s13, s56, s1
	s_add_i32 s0, s4, 0xffffe000
	s_cmpk_lt_i32 s4, 0x2000
	s_cselect_b32 s1, s5, 0
	s_cselect_b32 s0, s4, s0
	s_cselect_b32 s18, s15, s17
	s_cselect_b32 s19, s14, s16
	s_lshl_b64 s[0:1], s[0:1], 13
	s_add_u32 s0, s19, s0
	s_addc_u32 s1, s18, s1
	v_lshl_add_u64 v[2:3], v[206:207], 4, s[0:1]
	global_load_dwordx4 v[30:33], v[2:3], off nt
	global_load_dwordx4 v[26:29], v[2:3], off offset:1024 nt
	global_load_dwordx4 v[22:25], v[2:3], off offset:2048 nt
	global_load_dwordx4 v[18:21], v[2:3], off offset:3072 nt
	v_add_co_u32_e32 v2, vcc, s41, v2
	v_lshl_add_u64 v[54:55], v[38:39], 2, s[12:13]
	s_nop 0
	v_addc_co_u32_e32 v3, vcc, 0, v3, vcc
	global_load_dwordx4 v[14:17], v[2:3], off nt
	global_load_dwordx4 v[10:13], v[2:3], off offset:1024 nt
	global_load_dwordx4 v[6:9], v[2:3], off offset:2048 nt
	s_nop 0
	global_load_dwordx4 v[2:5], v[2:3], off offset:3072 nt
	v_lshl_add_u64 v[56:57], v[54:55], 0, s[44:45]
	v_add_co_u32_e32 v134, vcc, s20, v54
	s_nop 1
	v_addc_co_u32_e32 v135, vcc, 0, v55, vcc
	v_add_co_u32_e32 v154, vcc, s41, v54
	s_nop 1
	v_addc_co_u32_e32 v155, vcc, 0, v55, vcc
	global_load_dwordx4 v[158:161], v[40:41], off
	global_load_dwordx4 v[162:165], v[134:135], off offset:-4096
	global_load_dwordx4 v[166:169], v[54:55], off
	global_load_dwordx4 v[170:173], v[40:41], off offset:1024
	global_load_dwordx4 v[174:177], v[56:57], off offset:1024
	global_load_dwordx4 v[178:181], v[54:55], off offset:1024
	global_load_dwordx4 v[182:185], v[40:41], off offset:2048
	global_load_dwordx4 v[186:189], v[56:57], off offset:2048
	global_load_dwordx4 v[190:193], v[54:55], off offset:2048
	global_load_dwordx4 v[210:213], v[40:41], off offset:3072
	global_load_dwordx4 v[214:217], v[56:57], off offset:3072
	global_load_dwordx4 v[218:221], v[54:55], off offset:3072
	global_load_dwordx4 v[222:225], v[42:43], off
	global_load_dwordx4 v[240:243], v[134:135], off
	global_load_dwordx4 v[244:247], v[154:155], off
	global_load_dwordx4 v[138:141], v[44:45], off
	global_load_dwordx4 v[142:145], v[134:135], off offset:1024
	global_load_dwordx4 v[146:149], v[154:155], off offset:1024
	global_load_dwordx4 v[150:153], v[46:47], off
	global_load_dwordx4 v[72:75], v[134:135], off offset:2048
	global_load_dwordx4 v[76:79], v[154:155], off offset:2048
	global_load_dwordx4 v[80:83], v[48:49], off
	global_load_dwordx4 v[202:205], v[134:135], off offset:3072
	global_load_dwordx4 v[130:133], v[154:155], off offset:3072
	s_add_u32 s4, s4, s6
	s_addc_u32 s5, s5, s7
	s_waitcnt vmcnt(31)
	v_mov_b32_e32 v36, v31
	s_waitcnt vmcnt(30)
	v_mov_b32_e32 v37, v27
	v_mov_b32_e32 v34, v30
	v_mov_b32_e32 v35, v26
	v_pk_mul_f32 v[36:37], v[36:37], v[36:37]
	v_mov_b32_e32 v50, v33
	v_mov_b32_e32 v51, v29
	v_pk_fma_f32 v[34:35], v[34:35], v[34:35], v[36:37]
	v_mov_b32_e32 v36, v32
	v_mov_b32_e32 v37, v28
	v_pk_mul_f32 v[50:51], v[50:51], v[50:51]
	s_waitcnt vmcnt(27)
	v_mul_f32_e32 v0, v14, v14
	v_pk_fma_f32 v[36:37], v[36:37], v[36:37], v[50:51]
	v_pk_mul_f32 v[50:51], v[22:23], v[22:23]
	v_pk_add_f32 v[34:35], v[34:35], v[36:37]
	v_pk_mul_f32 v[36:37], v[24:25], v[24:25]
	v_pk_add_f32 v[34:35], v[34:35], v[34:35] op_sel:[0,1] op_sel_hi:[1,0]
	v_pk_mov_b32 v[52:53], v[50:51], v[36:37] op_sel:[1,0]
	v_mov_b32_e32 v51, v37
	v_pk_add_f32 v[36:37], v[52:53], v[50:51]
	v_mul_f32_e32 v50, v15, v15
	v_pk_add_f32 v[36:37], v[36:37], v[36:37] op_sel:[0,1] op_sel_hi:[1,0]
	v_mov_b32_e32 v35, v0
	v_mov_b32_e32 v37, v50
	v_mul_f32_e32 v0, v19, v19
	v_mul_f32_e32 v51, v16, v16
	v_pk_add_f32 v[34:35], v[34:35], v[36:37]
	v_pk_fma_f32 v[36:37], v[18:19], v[18:19], v[0:1] op_sel_hi:[1,1,0]
	v_mul_f32_e32 v0, v21, v21
	v_mul_f32_e32 v52, v17, v17
	v_mov_b32_e32 v37, v51
	v_pk_fma_f32 v[50:51], v[20:21], v[20:21], v[0:1] op_sel_hi:[1,1,0]
	s_waitcnt vmcnt(24)
	v_mul_f32_e32 v0, v2, v2
	v_mov_b32_e32 v51, v52
	v_pk_add_f32 v[36:37], v[36:37], v[50:51]
	v_pk_mul_f32 v[50:51], v[10:11], v[10:11]
	v_pk_add_f32 v[34:35], v[34:35], v[36:37]
	v_pk_mul_f32 v[36:37], v[12:13], v[12:13]
	v_pk_add_f32 v[34:35], v[34:35], v[34:35] op_sel:[0,1] op_sel_hi:[1,0]
	v_pk_mov_b32 v[52:53], v[50:51], v[36:37] op_sel:[1,0]
	v_mov_b32_e32 v51, v37
	v_pk_add_f32 v[36:37], v[52:53], v[50:51]
	v_mul_f32_e32 v50, v3, v3
	v_pk_add_f32 v[36:37], v[36:37], v[36:37] op_sel:[0,1] op_sel_hi:[1,0]
	v_mov_b32_e32 v35, v0
	v_mov_b32_e32 v37, v50
	v_mul_f32_e32 v0, v7, v7
	v_mul_f32_e32 v51, v4, v4
	v_pk_add_f32 v[34:35], v[34:35], v[36:37]
	v_pk_fma_f32 v[36:37], v[6:7], v[6:7], v[0:1] op_sel_hi:[1,1,0]
	v_mul_f32_e32 v0, v9, v9
	v_mul_f32_e32 v52, v5, v5
	v_mov_b32_e32 v37, v51
	v_pk_fma_f32 v[50:51], v[8:9], v[8:9], v[0:1] op_sel_hi:[1,1,0]
	s_nop 0
	v_mov_b32_e32 v51, v52
	v_pk_add_f32 v[36:37], v[36:37], v[50:51]
	s_nop 0
	v_pk_add_f32 v[34:35], v[34:35], v[36:37]
	s_nop 0
	v_add_f32_e32 v0, v34, v35
	ds_bpermute_b32 v34, v62, v0
	s_waitcnt lgkmcnt(0)
	v_add_f32_e32 v0, v0, v34
	ds_bpermute_b32 v34, v63, v0
	s_waitcnt lgkmcnt(0)
	v_add_f32_e32 v0, v0, v34
	ds_bpermute_b32 v34, v64, v0
	s_waitcnt lgkmcnt(0)
	v_add_f32_e32 v0, v0, v34
	ds_bpermute_b32 v34, v65, v0
	s_waitcnt lgkmcnt(0)
	v_add_f32_e32 v0, v0, v34
	ds_bpermute_b32 v34, v66, v0
	s_waitcnt lgkmcnt(0)
	v_add_f32_e32 v0, v0, v34
	ds_bpermute_b32 v34, v67, v0
	s_waitcnt lgkmcnt(0)
; #define GAS __attribute__((address_space(1)))
; DI unsigned pk2(float lo, float hi) { f32x2 v = {lo, hi}; bf16x2_t b = __builtin_convertvector(v, bf16x2_t); return __builtin_bit_cast(unsigned, b); }
; DI void phase_norm(const Ctx& C, const float* xlat, const float* xctx, bf16_t* H, const float* gn, const float* modl, int sh_off, int sc_off, int nrows, const float* part, int nsplit, float* xs_out) {
;     ...
;         const float rstd = 1.f / sqrtf(wave_sum(s, lane) * (1.f / DM) + EPS);
;         GAS u32x2* o8 = (GAS u32x2*)(H + (size_t)row * DM) + lane;
; #pragma unroll
;         for (int j = 0; j < 8; ++j) { const int col = 4 * lane + 256 * j;
;             const f32x4 g = *(const GAS f32x4*)(gn + col), sc = *(const GAS f32x4*)(mb + sc_off + col), sh = *(const GAS f32x4*)(mb + sh_off + col);
;             const f32x4 y = v[j] * rstd * g * (sc + 1.f) + sh;
;             u32x2 w; w.x = pk2(y.x, y.y); w.y = pk2(y.z, y.w); o8[64 * j] = w; }
	v_add_f32_e32 v0, v0, v34
	v_fmamk_f32 v0, v0, 0x3a000000, v227
	v_cmp_gt_f32_e32 vcc, s67, v0
	v_mul_f32_e32 v34, 0x4f800000, v0
	s_nop 0
	v_cndmask_b32_e32 v0, v0, v34, vcc
	v_sqrt_f32_e32 v34, v0
	s_nop 0
	v_add_u32_e32 v35, -1, v34
	v_fma_f32 v36, -v35, v34, v0
	v_cmp_ge_f32_e64 s[0:1], 0, v36
	v_add_u32_e32 v36, 1, v34
	s_nop 0
	v_cndmask_b32_e64 v35, v34, v35, s[0:1]
	v_fma_f32 v34, -v36, v34, v0
	v_cmp_lt_f32_e64 s[0:1], 0, v34
	s_nop 1
	v_cndmask_b32_e64 v34, v35, v36, s[0:1]
	v_mul_f32_e32 v35, 0x37800000, v34
	v_cndmask_b32_e32 v34, v34, v35, vcc
	v_cmp_class_f32_e32 vcc, v0, v228
	s_nop 1
	v_cndmask_b32_e32 v0, v34, v0, vcc
	v_div_scale_f32 v34, s[0:1], v0, v0, 1.0
	v_rcp_f32_e32 v35, v34
	s_nop 0
	v_fma_f32 v36, -v34, v35, 1.0
	v_fmac_f32_e32 v35, v36, v35
	v_div_scale_f32 v36, vcc, 1.0, v0, 1.0
	v_mul_f32_e32 v37, v36, v35
	v_fma_f32 v50, -v34, v37, v36
	v_fmac_f32_e32 v37, v50, v35
	v_fma_f32 v34, -v34, v37, v36
	v_div_fmas_f32 v34, v34, v35, v37
	v_div_fixup_f32 v0, v34, v0, 1.0
	s_nop 0
	v_pk_mul_f32 v[32:33], v[32:33], v[0:1] op_sel_hi:[1,0]
	v_pk_mul_f32 v[30:31], v[30:31], v[0:1] op_sel_hi:[1,0]
	s_waitcnt vmcnt(0)
	v_pk_mul_f32 v[32:33], v[160:161], v[32:33]
	v_pk_mul_f32 v[30:31], v[158:159], v[30:31]
	v_lshl_add_u64 v[50:51], v[206:207], 3, s[8:9]
	v_pk_mul_f32 v[28:29], v[28:29], v[0:1] op_sel_hi:[1,0]
	v_pk_mul_f32 v[26:27], v[26:27], v[0:1] op_sel_hi:[1,0]
	v_pk_mul_f32 v[24:25], v[24:25], v[0:1] op_sel_hi:[1,0]
	v_pk_mul_f32 v[22:23], v[22:23], v[0:1] op_sel_hi:[1,0]
	v_pk_mul_f32 v[20:21], v[20:21], v[0:1] op_sel_hi:[1,0]
	v_pk_mul_f32 v[18:19], v[18:19], v[0:1] op_sel_hi:[1,0]
	v_pk_mul_f32 v[16:17], v[16:17], v[0:1] op_sel_hi:[1,0]
	v_pk_mul_f32 v[14:15], v[14:15], v[0:1] op_sel_hi:[1,0]
	v_pk_mul_f32 v[12:13], v[12:13], v[0:1] op_sel_hi:[1,0]
	v_pk_mul_f32 v[10:11], v[10:11], v[0:1] op_sel_hi:[1,0]
	v_pk_mul_f32 v[8:9], v[8:9], v[0:1] op_sel_hi:[1,0]
	v_pk_mul_f32 v[6:7], v[6:7], v[0:1] op_sel_hi:[1,0]
	v_pk_mul_f32 v[4:5], v[4:5], v[0:1] op_sel_hi:[1,0]
	v_pk_mul_f32 v[2:3], v[2:3], v[0:1] op_sel_hi:[1,0]
	s_add_u32 s8, s8, s10
	s_addc_u32 s9, s9, s11
	s_cmpk_gt_i32 s4, 0x23ff
	v_pk_add_f32 v[58:59], v[164:165], 1.0 op_sel_hi:[1,0]
	v_pk_add_f32 v[60:61], v[162:163], 1.0 op_sel_hi:[1,0]
	v_pk_fma_f32 v[32:33], v[58:59], v[32:33], v[168:169]
	v_pk_fma_f32 v[30:31], v[60:61], v[30:31], v[166:167]
	s_nop 0
	v_cvt_pk_bf16_f32 v30, v30, v31
	v_cvt_pk_bf16_f32 v31, v32, v33
	global_store_dwordx2 v[50:51], v[30:31], off
	s_nop 0
	v_pk_mul_f32 v[26:27], v[170:171], v[26:27]
	v_pk_mul_f32 v[28:29], v[172:173], v[28:29]
	v_pk_add_f32 v[30:31], v[176:177], 1.0 op_sel_hi:[1,0]
	v_pk_add_f32 v[32:33], v[174:175], 1.0 op_sel_hi:[1,0]
	v_pk_fma_f32 v[28:29], v[30:31], v[28:29], v[180:181]
	v_pk_fma_f32 v[26:27], v[32:33], v[26:27], v[178:179]
	s_nop 0
	v_cvt_pk_bf16_f32 v26, v26, v27
	v_cvt_pk_bf16_f32 v27, v28, v29
	global_store_dwordx2 v[50:51], v[26:27], off offset:512
	s_nop 0
	v_pk_mul_f32 v[22:23], v[182:183], v[22:23]
	v_pk_mul_f32 v[24:25], v[184:185], v[24:25]
	v_pk_add_f32 v[26:27], v[188:189], 1.0 op_sel_hi:[1,0]
	v_pk_add_f32 v[28:29], v[186:187], 1.0 op_sel_hi:[1,0]
	v_pk_fma_f32 v[24:25], v[26:27], v[24:25], v[192:193]
	v_pk_fma_f32 v[22:23], v[28:29], v[22:23], v[190:191]
	s_nop 0
	v_cvt_pk_bf16_f32 v22, v22, v23
	v_cvt_pk_bf16_f32 v23, v24, v25
	global_store_dwordx2 v[50:51], v[22:23], off offset:1024
	s_nop 0
	v_pk_mul_f32 v[18:19], v[18:19], v[210:211]
	v_pk_mul_f32 v[20:21], v[20:21], v[212:213]
	v_pk_add_f32 v[22:23], v[216:217], 1.0 op_sel_hi:[1,0]
	v_pk_add_f32 v[24:25], v[214:215], 1.0 op_sel_hi:[1,0]
	v_pk_fma_f32 v[20:21], v[20:21], v[22:23], v[220:221]
	v_pk_fma_f32 v[18:19], v[18:19], v[24:25], v[218:219]
	s_nop 0
	v_cvt_pk_bf16_f32 v18, v18, v19
	v_cvt_pk_bf16_f32 v19, v20, v21
	global_store_dwordx2 v[50:51], v[18:19], off offset:1536
	s_nop 0
	v_pk_mul_f32 v[14:15], v[14:15], v[222:223]
	v_pk_mul_f32 v[16:17], v[16:17], v[224:225]
	v_pk_add_f32 v[18:19], v[242:243], 1.0 op_sel_hi:[1,0]
	v_pk_add_f32 v[20:21], v[240:241], 1.0 op_sel_hi:[1,0]
	v_pk_fma_f32 v[16:17], v[16:17], v[18:19], v[246:247]
	v_pk_fma_f32 v[14:15], v[14:15], v[20:21], v[244:245]
	s_nop 0
	v_cvt_pk_bf16_f32 v14, v14, v15
	v_cvt_pk_bf16_f32 v15, v16, v17
	global_store_dwordx2 v[50:51], v[14:15], off offset:2048
	s_nop 0
	v_pk_mul_f32 v[10:11], v[10:11], v[138:139]
	v_pk_mul_f32 v[12:13], v[12:13], v[140:141]
	v_pk_add_f32 v[14:15], v[144:145], 1.0 op_sel_hi:[1,0]
	v_pk_add_f32 v[16:17], v[142:143], 1.0 op_sel_hi:[1,0]
	v_pk_fma_f32 v[12:13], v[12:13], v[14:15], v[148:149]
	v_pk_fma_f32 v[10:11], v[10:11], v[16:17], v[146:147]
	s_nop 0
	v_cvt_pk_bf16_f32 v10, v10, v11
	v_cvt_pk_bf16_f32 v11, v12, v13
	global_store_dwordx2 v[50:51], v[10:11], off offset:2560
	s_nop 0
	v_pk_mul_f32 v[6:7], v[6:7], v[150:151]
	v_pk_mul_f32 v[8:9], v[8:9], v[152:153]
	v_pk_add_f32 v[10:11], v[74:75], 1.0 op_sel_hi:[1,0]
	v_pk_add_f32 v[12:13], v[72:73], 1.0 op_sel_hi:[1,0]
	v_pk_fma_f32 v[8:9], v[8:9], v[10:11], v[78:79]
	v_pk_fma_f32 v[6:7], v[6:7], v[12:13], v[76:77]
	s_nop 0
	v_cvt_pk_bf16_f32 v6, v6, v7
	v_cvt_pk_bf16_f32 v7, v8, v9
	global_store_dwordx2 v[50:51], v[6:7], off offset:3072
	s_nop 0
	v_pk_mul_f32 v[2:3], v[2:3], v[80:81]
	v_pk_mul_f32 v[4:5], v[4:5], v[82:83]
	v_pk_add_f32 v[6:7], v[204:205], 1.0 op_sel_hi:[1,0]
	v_pk_add_f32 v[8:9], v[202:203], 1.0 op_sel_hi:[1,0]
	v_pk_fma_f32 v[4:5], v[4:5], v[6:7], v[132:133]
	v_pk_fma_f32 v[2:3], v[2:3], v[8:9], v[130:131]
	s_nop 0
	v_cvt_pk_bf16_f32 v2, v2, v3
	v_cvt_pk_bf16_f32 v3, v4, v5
	global_store_dwordx2 v[50:51], v[2:3], off offset:3584
	s_cbranch_scc0 .LBB0_692
